# o30 + s_sleep 48 per pull in the GU1/GU2 conversion tails (lower peak HBM pressure on the GEMM tiles still running)
# speedup vs baseline: 1.0048x; 1.0048x over previous
.Lw1d_loop:
	v_readfirstlane_b32 s98, v18
	s_nop 3
	s_cmpk_ge_u32 s98, 0x780
	s_cbranch_scc1 .Lw1d_done
	s_cmpk_ge_u32 s98, 0x580
	s_cbranch_scc1 .Lwo_item
	s_lshr_b32 s99, s98, 4
	s_and_b32 s100, s98, 15
	s_lshl_b32 s101, s99, 19
	s_lshl_b32 s0, s100, 9
	s_add_u32 s0, s0, s101
	s_add_u32 s0, s8, s0
	s_addc_u32 s1, s9, 0
	s_mul_i32 s2, s100, 0x160000
	s_lshl_b32 s3, s99, 7
	s_add_u32 s2, s2, s3
	s_add_u32 s2, s2, 0x2d60200
	s_add_u32 s2, s86, s2
	s_addc_u32 s3, s87, 0
	s_add_u32 s4, s2, 0xb0000
	s_addc_u32 s5, s3, 0
	global_load_dwordx4 v[154:157], v8, s[0:1] nt
	global_load_dwordx4 v[204:207], v8, s[0:1] offset:256 nt
	s_add_u32 s0, s0, 0x2000
	s_addc_u32 s1, s1, 0
	global_load_dwordx4 v[158:161], v8, s[0:1] nt
	global_load_dwordx4 v[208:211], v8, s[0:1] offset:256 nt
	s_add_u32 s0, s0, 0x2000
	s_addc_u32 s1, s1, 0
	global_load_dwordx4 v[162:165], v8, s[0:1] nt
	global_load_dwordx4 v[212:215], v8, s[0:1] offset:256 nt
	s_add_u32 s0, s0, 0x2000
	s_addc_u32 s1, s1, 0
	global_load_dwordx4 v[166:169], v8, s[0:1] nt
	global_load_dwordx4 v[216:219], v8, s[0:1] offset:256 nt
	s_add_u32 s0, s0, 0x2000
	s_addc_u32 s1, s1, 0
	global_load_dwordx4 v[170:173], v8, s[0:1] nt
	global_load_dwordx4 v[220:223], v8, s[0:1] offset:256 nt
	s_add_u32 s0, s0, 0x2000
	s_addc_u32 s1, s1, 0
	global_load_dwordx4 v[174:177], v8, s[0:1] nt
	global_load_dwordx4 v[224:227], v8, s[0:1] offset:256 nt
	s_add_u32 s0, s0, 0x2000
	s_addc_u32 s1, s1, 0
	global_load_dwordx4 v[178:181], v8, s[0:1] nt
	global_load_dwordx4 v[228:231], v8, s[0:1] offset:256 nt
	s_add_u32 s0, s0, 0x2000
	s_addc_u32 s1, s1, 0
	global_load_dwordx4 v[182:185], v8, s[0:1] nt
	global_load_dwordx4 v[232:235], v8, s[0:1] offset:256 nt
	s_add_u32 s0, s0, 0x2000
	s_addc_u32 s1, s1, 0
	global_load_dwordx4 v[186:189], v8, s[0:1] nt
	global_load_dwordx4 v[236:239], v8, s[0:1] offset:256 nt
	s_add_u32 s0, s0, 0x2000
	s_addc_u32 s1, s1, 0
	global_load_dwordx4 v[190:193], v8, s[0:1] nt
	global_load_dwordx4 v[240:243], v8, s[0:1] offset:256 nt
	s_add_u32 s0, s0, 0x2000
	s_addc_u32 s1, s1, 0
	global_load_dwordx4 v[194:197], v8, s[0:1] nt
	global_load_dwordx4 v[244:247], v8, s[0:1] offset:256 nt
	s_add_u32 s0, s0, 0x2000
	s_addc_u32 s1, s1, 0
	global_load_dwordx4 v[198:201], v8, s[0:1] nt
	global_load_dwordx4 v[248:251], v8, s[0:1] offset:256 nt
	s_add_u32 s0, s0, 0x2000
	s_addc_u32 s1, s1, 0
	global_load_dwordx4 v[130:133], v8, s[0:1] nt
	global_load_dwordx4 v[50:53], v8, s[0:1] offset:256 nt
	s_add_u32 s0, s0, 0x2000
	s_addc_u32 s1, s1, 0
	global_load_dwordx4 v[134:137], v8, s[0:1] nt
	global_load_dwordx4 v[54:57], v8, s[0:1] offset:256 nt
	s_add_u32 s0, s0, 0x2000
	s_addc_u32 s1, s1, 0
	global_load_dwordx4 v[138:141], v8, s[0:1] nt
	global_load_dwordx4 v[58:61], v8, s[0:1] offset:256 nt
	s_add_u32 s0, s0, 0x2000
	s_addc_u32 s1, s1, 0
	global_load_dwordx4 v[142:145], v8, s[0:1] nt
	global_load_dwordx4 v[62:65], v8, s[0:1] offset:256 nt
	s_mov_b64 exec, 1
	global_atomic_add v18, v16, v17, s[6:7] sc0
	s_mov_b64 exec, -1
	s_waitcnt vmcnt(1)
	v_cvt_pk_bf16_f32 v20, v154, v158
	v_cvt_pk_bf16_f32 v21, v162, v166
	v_cvt_pk_bf16_f32 v22, v170, v174
	v_cvt_pk_bf16_f32 v23, v178, v182
	global_store_dwordx4 v12, v[20:23], s[2:3]
	v_cvt_pk_bf16_f32 v24, v186, v190
	v_cvt_pk_bf16_f32 v25, v194, v198
	v_cvt_pk_bf16_f32 v26, v130, v134
	v_cvt_pk_bf16_f32 v27, v138, v142
	global_store_dwordx4 v12, v[24:27], s[2:3] offset:16
	v_cvt_pk_bf16_f32 v28, v155, v159
	v_cvt_pk_bf16_f32 v29, v163, v167
	v_cvt_pk_bf16_f32 v30, v171, v175
	v_cvt_pk_bf16_f32 v31, v179, v183
	global_store_dwordx4 v13, v[28:31], s[2:3]
	v_cvt_pk_bf16_f32 v32, v187, v191
	v_cvt_pk_bf16_f32 v33, v195, v199
	v_cvt_pk_bf16_f32 v34, v131, v135
	v_cvt_pk_bf16_f32 v35, v139, v143
	global_store_dwordx4 v13, v[32:35], s[2:3] offset:16
	v_cvt_pk_bf16_f32 v36, v156, v160
	v_cvt_pk_bf16_f32 v37, v164, v168
	v_cvt_pk_bf16_f32 v38, v172, v176
	v_cvt_pk_bf16_f32 v39, v180, v184
	global_store_dwordx4 v14, v[36:39], s[2:3]
	v_cvt_pk_bf16_f32 v40, v188, v192
	v_cvt_pk_bf16_f32 v41, v196, v200
	v_cvt_pk_bf16_f32 v42, v132, v136
	v_cvt_pk_bf16_f32 v43, v140, v144
	global_store_dwordx4 v14, v[40:43], s[2:3] offset:16
	v_cvt_pk_bf16_f32 v20, v157, v161
	v_cvt_pk_bf16_f32 v21, v165, v169
	v_cvt_pk_bf16_f32 v22, v173, v177
	v_cvt_pk_bf16_f32 v23, v181, v185
	global_store_dwordx4 v15, v[20:23], s[2:3]
	v_cvt_pk_bf16_f32 v24, v189, v193
	v_cvt_pk_bf16_f32 v25, v197, v201
	v_cvt_pk_bf16_f32 v26, v133, v137
	v_cvt_pk_bf16_f32 v27, v141, v145
	global_store_dwordx4 v15, v[24:27], s[2:3] offset:16
	v_cvt_pk_bf16_f32 v28, v204, v208
	v_cvt_pk_bf16_f32 v29, v212, v216
	v_cvt_pk_bf16_f32 v30, v220, v224
	v_cvt_pk_bf16_f32 v31, v228, v232
	global_store_dwordx4 v12, v[28:31], s[4:5]
	v_cvt_pk_bf16_f32 v32, v236, v240
	v_cvt_pk_bf16_f32 v33, v244, v248
	v_cvt_pk_bf16_f32 v34, v50, v54
	v_cvt_pk_bf16_f32 v35, v58, v62
	global_store_dwordx4 v12, v[32:35], s[4:5] offset:16
	v_cvt_pk_bf16_f32 v36, v205, v209
	v_cvt_pk_bf16_f32 v37, v213, v217
	v_cvt_pk_bf16_f32 v38, v221, v225
	v_cvt_pk_bf16_f32 v39, v229, v233
	global_store_dwordx4 v13, v[36:39], s[4:5]
	v_cvt_pk_bf16_f32 v40, v237, v241
	v_cvt_pk_bf16_f32 v41, v245, v249
	v_cvt_pk_bf16_f32 v42, v51, v55
	v_cvt_pk_bf16_f32 v43, v59, v63
	global_store_dwordx4 v13, v[40:43], s[4:5] offset:16
	v_cvt_pk_bf16_f32 v20, v206, v210
	v_cvt_pk_bf16_f32 v21, v214, v218
	v_cvt_pk_bf16_f32 v22, v222, v226
	v_cvt_pk_bf16_f32 v23, v230, v234
	global_store_dwordx4 v14, v[20:23], s[4:5]
	v_cvt_pk_bf16_f32 v24, v238, v242
	v_cvt_pk_bf16_f32 v25, v246, v250
	v_cvt_pk_bf16_f32 v26, v52, v56
	v_cvt_pk_bf16_f32 v27, v60, v64
	global_store_dwordx4 v14, v[24:27], s[4:5] offset:16
	v_cvt_pk_bf16_f32 v28, v207, v211
	v_cvt_pk_bf16_f32 v29, v215, v219
	v_cvt_pk_bf16_f32 v30, v223, v227
	v_cvt_pk_bf16_f32 v31, v231, v235
	global_store_dwordx4 v15, v[28:31], s[4:5]
	v_cvt_pk_bf16_f32 v32, v239, v243
	v_cvt_pk_bf16_f32 v33, v247, v251
	v_cvt_pk_bf16_f32 v34, v53, v57
	v_cvt_pk_bf16_f32 v35, v61, v65
	global_store_dwordx4 v15, v[32:35], s[4:5] offset:16
	s_sleep 48
	s_waitcnt vmcnt(16)
	s_branch .Lw1d_loop
.Lwo_item:
	s_sub_u32 s98, s98, 0x580
	s_lshr_b32 s99, s98, 4
	s_and_b32 s100, s98, 15
	s_lshl_b32 s101, s99, 19
	s_lshl_b32 s0, s100, 9
	s_add_u32 s0, s0, s101
	s_add_u32 s0, s10, s0
	s_addc_u32 s1, s11, 0
	s_lshl_b32 s2, s100, 19
	s_lshl_b32 s3, s99, 7
	s_add_u32 s2, s2, s3
	s_add_u32 s2, s2, 0x8460200
	s_add_u32 s2, s86, s2
	s_addc_u32 s3, s87, 0
	s_add_u32 s4, s2, 0x40000
	s_addc_u32 s5, s3, 0
	global_load_dwordx4 v[154:157], v8, s[0:1] nt
	global_load_dwordx4 v[204:207], v8, s[0:1] offset:256 nt
	s_add_u32 s0, s0, 0x2000
	s_addc_u32 s1, s1, 0
	global_load_dwordx4 v[158:161], v8, s[0:1] nt
	global_load_dwordx4 v[208:211], v8, s[0:1] offset:256 nt
	s_add_u32 s0, s0, 0x2000
	s_addc_u32 s1, s1, 0
	global_load_dwordx4 v[162:165], v8, s[0:1] nt
	global_load_dwordx4 v[212:215], v8, s[0:1] offset:256 nt
	s_add_u32 s0, s0, 0x2000
	s_addc_u32 s1, s1, 0
	global_load_dwordx4 v[166:169], v8, s[0:1] nt
	global_load_dwordx4 v[216:219], v8, s[0:1] offset:256 nt
	s_add_u32 s0, s0, 0x2000
	s_addc_u32 s1, s1, 0
	global_load_dwordx4 v[170:173], v8, s[0:1] nt
	global_load_dwordx4 v[220:223], v8, s[0:1] offset:256 nt
	s_add_u32 s0, s0, 0x2000
	s_addc_u32 s1, s1, 0
	global_load_dwordx4 v[174:177], v8, s[0:1] nt
	global_load_dwordx4 v[224:227], v8, s[0:1] offset:256 nt
	s_add_u32 s0, s0, 0x2000
	s_addc_u32 s1, s1, 0
	global_load_dwordx4 v[178:181], v8, s[0:1] nt
	global_load_dwordx4 v[228:231], v8, s[0:1] offset:256 nt
	s_add_u32 s0, s0, 0x2000
	s_addc_u32 s1, s1, 0
	global_load_dwordx4 v[182:185], v8, s[0:1] nt
	global_load_dwordx4 v[232:235], v8, s[0:1] offset:256 nt
	s_add_u32 s0, s0, 0x2000
	s_addc_u32 s1, s1, 0
	global_load_dwordx4 v[186:189], v8, s[0:1] nt
	global_load_dwordx4 v[236:239], v8, s[0:1] offset:256 nt
	s_add_u32 s0, s0, 0x2000
	s_addc_u32 s1, s1, 0
	global_load_dwordx4 v[190:193], v8, s[0:1] nt
	global_load_dwordx4 v[240:243], v8, s[0:1] offset:256 nt
	s_add_u32 s0, s0, 0x2000
	s_addc_u32 s1, s1, 0
	global_load_dwordx4 v[194:197], v8, s[0:1] nt
	global_load_dwordx4 v[244:247], v8, s[0:1] offset:256 nt
	s_add_u32 s0, s0, 0x2000
	s_addc_u32 s1, s1, 0
	global_load_dwordx4 v[198:201], v8, s[0:1] nt
	global_load_dwordx4 v[248:251], v8, s[0:1] offset:256 nt
	s_add_u32 s0, s0, 0x2000
	s_addc_u32 s1, s1, 0
	global_load_dwordx4 v[130:133], v8, s[0:1] nt
	global_load_dwordx4 v[50:53], v8, s[0:1] offset:256 nt
	s_add_u32 s0, s0, 0x2000
	s_addc_u32 s1, s1, 0
	global_load_dwordx4 v[134:137], v8, s[0:1] nt
	global_load_dwordx4 v[54:57], v8, s[0:1] offset:256 nt
	s_add_u32 s0, s0, 0x2000
	s_addc_u32 s1, s1, 0
	global_load_dwordx4 v[138:141], v8, s[0:1] nt
	global_load_dwordx4 v[58:61], v8, s[0:1] offset:256 nt
	s_add_u32 s0, s0, 0x2000
	s_addc_u32 s1, s1, 0
	global_load_dwordx4 v[142:145], v8, s[0:1] nt
	global_load_dwordx4 v[62:65], v8, s[0:1] offset:256 nt
	s_mov_b64 exec, 1
	global_atomic_add v18, v16, v17, s[6:7] sc0
	s_mov_b64 exec, -1
	s_waitcnt vmcnt(1)
	v_cvt_pk_bf16_f32 v20, v154, v158
	v_cvt_pk_bf16_f32 v21, v162, v166
	v_cvt_pk_bf16_f32 v22, v170, v174
	v_cvt_pk_bf16_f32 v23, v178, v182
	global_store_dwordx4 v44, v[20:23], s[2:3]
	v_cvt_pk_bf16_f32 v24, v186, v190
	v_cvt_pk_bf16_f32 v25, v194, v198
	v_cvt_pk_bf16_f32 v26, v130, v134
	v_cvt_pk_bf16_f32 v27, v138, v142
	global_store_dwordx4 v44, v[24:27], s[2:3] offset:16
	v_cvt_pk_bf16_f32 v28, v155, v159
	v_cvt_pk_bf16_f32 v29, v163, v167
	v_cvt_pk_bf16_f32 v30, v171, v175
	v_cvt_pk_bf16_f32 v31, v179, v183
	global_store_dwordx4 v45, v[28:31], s[2:3]
	v_cvt_pk_bf16_f32 v32, v187, v191
	v_cvt_pk_bf16_f32 v33, v195, v199
	v_cvt_pk_bf16_f32 v34, v131, v135
	v_cvt_pk_bf16_f32 v35, v139, v143
	global_store_dwordx4 v45, v[32:35], s[2:3] offset:16
	v_cvt_pk_bf16_f32 v36, v156, v160
	v_cvt_pk_bf16_f32 v37, v164, v168
	v_cvt_pk_bf16_f32 v38, v172, v176
	v_cvt_pk_bf16_f32 v39, v180, v184
	global_store_dwordx4 v46, v[36:39], s[2:3]
	v_cvt_pk_bf16_f32 v40, v188, v192
	v_cvt_pk_bf16_f32 v41, v196, v200
	v_cvt_pk_bf16_f32 v42, v132, v136
	v_cvt_pk_bf16_f32 v43, v140, v144
	global_store_dwordx4 v46, v[40:43], s[2:3] offset:16
	v_cvt_pk_bf16_f32 v20, v157, v161
	v_cvt_pk_bf16_f32 v21, v165, v169
	v_cvt_pk_bf16_f32 v22, v173, v177
	v_cvt_pk_bf16_f32 v23, v181, v185
	global_store_dwordx4 v47, v[20:23], s[2:3]
	v_cvt_pk_bf16_f32 v24, v189, v193
	v_cvt_pk_bf16_f32 v25, v197, v201
	v_cvt_pk_bf16_f32 v26, v133, v137
	v_cvt_pk_bf16_f32 v27, v141, v145
	global_store_dwordx4 v47, v[24:27], s[2:3] offset:16
	v_cvt_pk_bf16_f32 v28, v204, v208
	v_cvt_pk_bf16_f32 v29, v212, v216
	v_cvt_pk_bf16_f32 v30, v220, v224
	v_cvt_pk_bf16_f32 v31, v228, v232
	global_store_dwordx4 v44, v[28:31], s[4:5]
	v_cvt_pk_bf16_f32 v32, v236, v240
	v_cvt_pk_bf16_f32 v33, v244, v248
	v_cvt_pk_bf16_f32 v34, v50, v54
	v_cvt_pk_bf16_f32 v35, v58, v62
	global_store_dwordx4 v44, v[32:35], s[4:5] offset:16
	v_cvt_pk_bf16_f32 v36, v205, v209
	v_cvt_pk_bf16_f32 v37, v213, v217
	v_cvt_pk_bf16_f32 v38, v221, v225
	v_cvt_pk_bf16_f32 v39, v229, v233
	global_store_dwordx4 v45, v[36:39], s[4:5]
	v_cvt_pk_bf16_f32 v40, v237, v241
	v_cvt_pk_bf16_f32 v41, v245, v249
	v_cvt_pk_bf16_f32 v42, v51, v55
	v_cvt_pk_bf16_f32 v43, v59, v63
	global_store_dwordx4 v45, v[40:43], s[4:5] offset:16
	v_cvt_pk_bf16_f32 v20, v206, v210
	v_cvt_pk_bf16_f32 v21, v214, v218
	v_cvt_pk_bf16_f32 v22, v222, v226
	v_cvt_pk_bf16_f32 v23, v230, v234
	global_store_dwordx4 v46, v[20:23], s[4:5]
	v_cvt_pk_bf16_f32 v24, v238, v242
	v_cvt_pk_bf16_f32 v25, v246, v250
	v_cvt_pk_bf16_f32 v26, v52, v56
	v_cvt_pk_bf16_f32 v27, v60, v64
	global_store_dwordx4 v46, v[24:27], s[4:5] offset:16
	v_cvt_pk_bf16_f32 v28, v207, v211
	v_cvt_pk_bf16_f32 v29, v215, v219
	v_cvt_pk_bf16_f32 v30, v223, v227
	v_cvt_pk_bf16_f32 v31, v231, v235
	global_store_dwordx4 v47, v[28:31], s[4:5]
	v_cvt_pk_bf16_f32 v32, v239, v243
	v_cvt_pk_bf16_f32 v33, v247, v251
	v_cvt_pk_bf16_f32 v34, v53, v57
	v_cvt_pk_bf16_f32 v35, v61, v65
	global_store_dwordx4 v47, v[32:35], s[4:5] offset:16
	s_sleep 48
	s_waitcnt vmcnt(16)
	s_branch .Lw1d_loop

.Lw2d_loop:
	v_readfirstlane_b32 s98, v18
	s_nop 3
	s_cmpk_ge_u32 s98, 0x580
	s_cbranch_scc1 .Lw2d_done
	s_lshr_b32 s99, s98, 4
	s_and_b32 s100, s98, 15
	s_lshl_b32 s101, s99, 19
	s_lshl_b32 s0, s100, 9
	s_add_u32 s0, s0, s101
	s_add_u32 s0, s10, s0
	s_addc_u32 s1, s11, 0
	s_mul_i32 s2, s100, 0x160000
	s_lshl_b32 s3, s99, 7
	s_add_u32 s2, s2, s3
	s_add_u32 s2, s2, 0xb860200
	s_add_u32 s2, s86, s2
	s_addc_u32 s3, s87, 0
	s_add_u32 s6, s2, 0xb0000
	s_addc_u32 s7, s3, 0
	global_load_dwordx4 v[154:157], v8, s[0:1] nt
	global_load_dwordx4 v[204:207], v8, s[0:1] offset:256 nt
	s_add_u32 s0, s0, 0x2000
	s_addc_u32 s1, s1, 0
	global_load_dwordx4 v[158:161], v8, s[0:1] nt
	global_load_dwordx4 v[208:211], v8, s[0:1] offset:256 nt
	s_add_u32 s0, s0, 0x2000
	s_addc_u32 s1, s1, 0
	global_load_dwordx4 v[162:165], v8, s[0:1] nt
	global_load_dwordx4 v[212:215], v8, s[0:1] offset:256 nt
	s_add_u32 s0, s0, 0x2000
	s_addc_u32 s1, s1, 0
	global_load_dwordx4 v[166:169], v8, s[0:1] nt
	global_load_dwordx4 v[216:219], v8, s[0:1] offset:256 nt
	s_add_u32 s0, s0, 0x2000
	s_addc_u32 s1, s1, 0
	global_load_dwordx4 v[170:173], v8, s[0:1] nt
	global_load_dwordx4 v[220:223], v8, s[0:1] offset:256 nt
	s_add_u32 s0, s0, 0x2000
	s_addc_u32 s1, s1, 0
	global_load_dwordx4 v[174:177], v8, s[0:1] nt
	global_load_dwordx4 v[224:227], v8, s[0:1] offset:256 nt
	s_add_u32 s0, s0, 0x2000
	s_addc_u32 s1, s1, 0
	global_load_dwordx4 v[178:181], v8, s[0:1] nt
	global_load_dwordx4 v[228:231], v8, s[0:1] offset:256 nt
	s_add_u32 s0, s0, 0x2000
	s_addc_u32 s1, s1, 0
	global_load_dwordx4 v[182:185], v8, s[0:1] nt
	global_load_dwordx4 v[232:235], v8, s[0:1] offset:256 nt
	s_add_u32 s0, s0, 0x2000
	s_addc_u32 s1, s1, 0
	global_load_dwordx4 v[186:189], v8, s[0:1] nt
	global_load_dwordx4 v[236:239], v8, s[0:1] offset:256 nt
	s_add_u32 s0, s0, 0x2000
	s_addc_u32 s1, s1, 0
	global_load_dwordx4 v[190:193], v8, s[0:1] nt
	global_load_dwordx4 v[240:243], v8, s[0:1] offset:256 nt
	s_add_u32 s0, s0, 0x2000
	s_addc_u32 s1, s1, 0
	global_load_dwordx4 v[194:197], v8, s[0:1] nt
	global_load_dwordx4 v[244:247], v8, s[0:1] offset:256 nt
	s_add_u32 s0, s0, 0x2000
	s_addc_u32 s1, s1, 0
	global_load_dwordx4 v[198:201], v8, s[0:1] nt
	global_load_dwordx4 v[248:251], v8, s[0:1] offset:256 nt
	s_add_u32 s0, s0, 0x2000
	s_addc_u32 s1, s1, 0
	global_load_dwordx4 v[130:133], v8, s[0:1] nt
	global_load_dwordx4 v[50:53], v8, s[0:1] offset:256 nt
	s_add_u32 s0, s0, 0x2000
	s_addc_u32 s1, s1, 0
	global_load_dwordx4 v[134:137], v8, s[0:1] nt
	global_load_dwordx4 v[54:57], v8, s[0:1] offset:256 nt
	s_add_u32 s0, s0, 0x2000
	s_addc_u32 s1, s1, 0
	global_load_dwordx4 v[138:141], v8, s[0:1] nt
	global_load_dwordx4 v[58:61], v8, s[0:1] offset:256 nt
	s_add_u32 s0, s0, 0x2000
	s_addc_u32 s1, s1, 0
	global_load_dwordx4 v[142:145], v8, s[0:1] nt
	global_load_dwordx4 v[62:65], v8, s[0:1] offset:256 nt
	s_mov_b64 exec, 1
	global_atomic_add v18, v16, v17, s[8:9] sc0
	s_mov_b64 exec, -1
	s_waitcnt vmcnt(1)
	v_cvt_pk_bf16_f32 v20, v154, v158
	v_cvt_pk_bf16_f32 v21, v162, v166
	v_cvt_pk_bf16_f32 v22, v170, v174
	v_cvt_pk_bf16_f32 v23, v178, v182
	global_store_dwordx4 v12, v[20:23], s[2:3]
	v_cvt_pk_bf16_f32 v24, v186, v190
	v_cvt_pk_bf16_f32 v25, v194, v198
	v_cvt_pk_bf16_f32 v26, v130, v134
	v_cvt_pk_bf16_f32 v27, v138, v142
	global_store_dwordx4 v12, v[24:27], s[2:3] offset:16
	v_cvt_pk_bf16_f32 v28, v155, v159
	v_cvt_pk_bf16_f32 v29, v163, v167
	v_cvt_pk_bf16_f32 v30, v171, v175
	v_cvt_pk_bf16_f32 v31, v179, v183
	global_store_dwordx4 v13, v[28:31], s[2:3]
	v_cvt_pk_bf16_f32 v32, v187, v191
	v_cvt_pk_bf16_f32 v33, v195, v199
	v_cvt_pk_bf16_f32 v34, v131, v135
	v_cvt_pk_bf16_f32 v35, v139, v143
	global_store_dwordx4 v13, v[32:35], s[2:3] offset:16
	v_cvt_pk_bf16_f32 v36, v156, v160
	v_cvt_pk_bf16_f32 v37, v164, v168
	v_cvt_pk_bf16_f32 v38, v172, v176
	v_cvt_pk_bf16_f32 v39, v180, v184
	global_store_dwordx4 v14, v[36:39], s[2:3]
	v_cvt_pk_bf16_f32 v40, v188, v192
	v_cvt_pk_bf16_f32 v41, v196, v200
	v_cvt_pk_bf16_f32 v42, v132, v136
	v_cvt_pk_bf16_f32 v43, v140, v144
	global_store_dwordx4 v14, v[40:43], s[2:3] offset:16
	v_cvt_pk_bf16_f32 v20, v157, v161
	v_cvt_pk_bf16_f32 v21, v165, v169
	v_cvt_pk_bf16_f32 v22, v173, v177
	v_cvt_pk_bf16_f32 v23, v181, v185
	global_store_dwordx4 v15, v[20:23], s[2:3]
	v_cvt_pk_bf16_f32 v24, v189, v193
	v_cvt_pk_bf16_f32 v25, v197, v201
	v_cvt_pk_bf16_f32 v26, v133, v137
	v_cvt_pk_bf16_f32 v27, v141, v145
	global_store_dwordx4 v15, v[24:27], s[2:3] offset:16
	v_cvt_pk_bf16_f32 v28, v204, v208
	v_cvt_pk_bf16_f32 v29, v212, v216
	v_cvt_pk_bf16_f32 v30, v220, v224
	v_cvt_pk_bf16_f32 v31, v228, v232
	global_store_dwordx4 v12, v[28:31], s[6:7]
	v_cvt_pk_bf16_f32 v32, v236, v240
	v_cvt_pk_bf16_f32 v33, v244, v248
	v_cvt_pk_bf16_f32 v34, v50, v54
	v_cvt_pk_bf16_f32 v35, v58, v62
	global_store_dwordx4 v12, v[32:35], s[6:7] offset:16
	v_cvt_pk_bf16_f32 v36, v205, v209
	v_cvt_pk_bf16_f32 v37, v213, v217
	v_cvt_pk_bf16_f32 v38, v221, v225
	v_cvt_pk_bf16_f32 v39, v229, v233
	global_store_dwordx4 v13, v[36:39], s[6:7]
	v_cvt_pk_bf16_f32 v40, v237, v241
	v_cvt_pk_bf16_f32 v41, v245, v249
	v_cvt_pk_bf16_f32 v42, v51, v55
	v_cvt_pk_bf16_f32 v43, v59, v63
	global_store_dwordx4 v13, v[40:43], s[6:7] offset:16
	v_cvt_pk_bf16_f32 v20, v206, v210
	v_cvt_pk_bf16_f32 v21, v214, v218
	v_cvt_pk_bf16_f32 v22, v222, v226
	v_cvt_pk_bf16_f32 v23, v230, v234
	global_store_dwordx4 v14, v[20:23], s[6:7]
	v_cvt_pk_bf16_f32 v24, v238, v242
	v_cvt_pk_bf16_f32 v25, v246, v250
	v_cvt_pk_bf16_f32 v26, v52, v56
	v_cvt_pk_bf16_f32 v27, v60, v64
	global_store_dwordx4 v14, v[24:27], s[6:7] offset:16
	v_cvt_pk_bf16_f32 v28, v207, v211
	v_cvt_pk_bf16_f32 v29, v215, v219
	v_cvt_pk_bf16_f32 v30, v223, v227
	v_cvt_pk_bf16_f32 v31, v231, v235
	global_store_dwordx4 v15, v[28:31], s[6:7]
	v_cvt_pk_bf16_f32 v32, v239, v243
	v_cvt_pk_bf16_f32 v33, v247, v251
	v_cvt_pk_bf16_f32 v34, v53, v57
	v_cvt_pk_bf16_f32 v35, v61, v65
	global_store_dwordx4 v15, v[32:35], s[6:7] offset:16
	s_sleep 48
	s_waitcnt vmcnt(16)
	s_branch .Lw2d_loop
